# bar_nowb + x-tile prefetch (126 rows) by waves 1-7 during the P3->P4 grid barrier
# baseline (speedup 1.0000x reference)
.LBB0_434:
	s_cmp_gt_i32 s83, 4
	s_cselect_b64 s[0:1], -1, 0
	s_and_b64 s[4:5], s[6:7], s[0:1]
	s_andn2_b64 vcc, exec, s[4:5]
	s_cbranch_vccnz .LBB0_488
	s_waitcnt vmcnt(0)
	s_waitcnt vmcnt(0)
	s_barrier
	s_cmpk_lg_i32 s3, 0x100
	s_cbranch_scc1 .Lb3pf_skip
	v_readfirstlane_b32 s6, v216
	s_lshr_b32 s6, s6, 6
	s_cmp_eq_u32 s6, 0
	s_cbranch_scc1 .Lb3pf_skip
	s_add_i32 s6, s6, -1
	s_mul_i32 s6, s6, 0x12000
	s_and_b32 s7, s2, 7
	s_lshl_b32 s7, s7, 3
	s_bfe_u32 s8, s2, 0x30003
	s_or_b32 s7, s7, s8
	s_lshl_b32 s7, s7, 20
	s_add_u32 s6, s6, s7
	s_lshr_b32 s7, s2, 6
	s_lshl_b32 s7, s7, 10
	s_add_u32 s6, s6, s7
	s_add_u32 s8, s40, s6
	s_addc_u32 s9, s41, 0
	v_and_b32_e32 v1, 63, v216
	v_lshlrev_b32_e32 v1, 4, v1
	s_mov_b32 m0, 0x22000
	s_movk_i32 s10, 18
.Lb3pf_loop:
	global_load_lds_dwordx4 v1, s[8:9]
	s_add_u32 s8, s8, 0x1000
	s_addc_u32 s9, s9, 0
	s_add_i32 s10, s10, -1
	s_cmp_lg_u32 s10, 0
	s_cbranch_scc1 .Lb3pf_loop
.Lb3pf_skip:
	s_and_saveexec_b64 s[4:5], s[94:95]
	s_cbranch_execz .LBB0_487
	s_add_i32 s6, 0, 0x23ff0
	v_mov_b32_e32 v0, s6
	s_waitcnt vmcnt(0) expcnt(0) lgkmcnt(0)
	ds_read_b32 v2, v0
	s_add_i32 s6, 0, 0x23ff4
	v_mov_b32_e32 v0, s6
	ds_read_b32 v0, v0
	s_waitcnt lgkmcnt(1)
	v_cmp_ne_u32_e32 vcc, 0, v2
	s_cbranch_vccnz .LBB0_451
	s_load_dwordx2 s[10:11], s[92:93], 0x4
	s_add_u32 s6, s80, 0x2380200
	s_addc_u32 s7, s81, 0
	s_add_u32 s8, s80, 0x2380400
	s_addc_u32 s9, s81, 0
	s_waitcnt lgkmcnt(0)
	s_mul_i32 s33, s10, s3
	s_add_u32 s10, s80, 0x2380500
	s_mul_i32 s33, s33, s11
	s_addc_u32 s11, s81, 0
	s_add_u32 s12, s80, 0x2380600
	s_addc_u32 s13, s81, 0
	s_add_u32 s14, s80, 0x2380700
	s_addc_u32 s15, s81, 0
	s_add_u32 s16, s80, 0x2380800
	s_addc_u32 s17, s81, 0
	s_add_u32 s18, s80, 0x2380900
	s_addc_u32 s19, s81, 0
	s_add_u32 s20, s80, 0x2380a00
	s_addc_u32 s21, s81, 0
	s_add_u32 s22, s80, 0x2380b00
	s_addc_u32 s23, s81, 0
	s_add_u32 s24, s80, 0x2380c00
	s_addc_u32 s25, s81, 0
	s_add_u32 s26, s80, 0x2380d00
	s_addc_u32 s27, s81, 0
	s_add_u32 s28, s80, 0x2380e00
	s_addc_u32 s29, s81, 0
	s_add_u32 s30, s80, 0x2380f00
	s_addc_u32 s31, s81, 0
	s_add_u32 s34, s80, 0x2381000
	s_addc_u32 s35, s81, 0
	s_add_u32 s36, s80, 0x2381100
	s_addc_u32 s37, s81, 0
	s_add_u32 s38, s80, 0x2381200
	s_addc_u32 s39, s81, 0
	s_add_u32 s42, s80, 0x2381300
	s_addc_u32 s43, s81, 0
	s_mov_b32 s50, 1
	v_mov_b32_e32 v16, 0
	s_branch .LBB0_439
